# attention work queue serves longest units first: the 2048 short units (chunks 0..3) are handed out last to shorten the P4 tail
# speedup vs baseline: 1.0077x; 1.0077x over previous
.LBB0_801:
	s_or_b64 exec, exec, s[12:13]
	v_readfirstlane_b32 s43, v0
	s_cmpk_gt_i32 s43, 0x3fff
	s_mov_b64 s[12:13], -1
	s_cbranch_scc1 .LBB0_796
	s_cmpk_lt_u32 s43, 0x3800
	s_cbranch_scc0 .Lq_tail
	s_mul_hi_u32 s12, s43, 0x4924925
	s_mul_i32 s13, s12, 56
	s_sub_i32 s13, s43, s13
	s_add_i32 s13, s13, 8
	s_lshl_b32 s12, s12, 6
	s_or_b32 s43, s12, s13
	s_branch .Lq_mapped
.Lq_tail:
	s_sub_i32 s13, s43, 0x3800
	s_bfe_u32 s12, s13, 0x80001
	s_lshr_b32 s14, s13, 9
	s_sub_i32 s14, 3, s14
	s_and_b32 s13, s13, 1
	s_lshl_b32 s12, s12, 6
	s_lshl_b32 s14, s14, 1
	s_or_b32 s12, s12, s14
	s_or_b32 s43, s12, s13
.Lq_mapped:
	s_ashr_i32 s12, s43, 9
	s_bfe_u32 s52, s43, 0x50001
	s_ashr_i32 s13, s12, 31
	s_lshl_b32 s14, s43, 5
	s_lshl_b64 s[20:21], s[12:13], 11
	s_lshl_b32 s13, s52, 6
	s_and_b32 s25, s14, 32
	s_or_b32 s13, s13, s25
	v_or_b32_e32 v0, s13, v180
	v_or_b32_e32 v2, s20, v0
	v_mov_b64_e32 v[0:1], s[50:51]
	v_mad_u64_u32 v[2:3], s[40:41], v2, s17, v[0:1]
	v_sub_u32_e64 v4, 8, s52 clamp
	s_bfe_u32 s42, s43, 0x30006
	s_add_i32 s41, s52, -8
	v_readfirstlane_b32 s13, v4
	s_mul_i32 s24, s42, 0x404
	s_add_i32 s54, s41, s13
	v_mad_i32_i24 v3, s21, v227, v3
	s_lshl_b32 s14, s42, 7
	s_add_i32 s24, s24, 0
	s_ashr_i32 s55, s54, 31
	v_lshl_add_u64 v[192:193], v[2:3], 0, s[14:15]
	s_add_i32 s24, s24, 0x20000
	s_lshl_b64 s[54:55], s[54:55], 6
	v_lshl_add_u64 v[2:3], v[192:193], 0, v[182:183]
	s_add_u32 s13, s54, s20
	global_load_dwordx4 v[108:111], v[2:3], off
	global_load_dwordx4 v[104:107], v[2:3], off offset:32
	global_load_dwordx4 v[100:103], v[2:3], off offset:64
	global_load_dwordx4 v[96:99], v[2:3], off offset:96
	v_or_b32_e32 v2, s13, v180
	s_addc_u32 s40, s55, s21
	v_mad_u64_u32 v[0:1], s[54:55], v2, s17, v[0:1]
	v_mad_i32_i24 v1, s40, v227, v1
	v_lshl_add_u64 v[0:1], v[0:1], 0, s[14:15]
	v_lshl_add_u64 v[0:1], v[0:1], 0, v[182:183]
	v_add_co_u32_e32 v2, vcc, s26, v0
	v_readfirstlane_b32 s40, v4
	s_nop 0
	v_addc_co_u32_e32 v3, vcc, 0, v1, vcc
	global_load_dwordx4 v[52:55], v[0:1], off offset:1024
	global_load_dwordx4 v[48:51], v[0:1], off offset:1056
	global_load_dwordx4 v[56:59], v[2:3], off offset:1024
	global_load_dwordx4 v[44:47], v[2:3], off offset:1056
	global_load_dwordx4 v[40:43], v[0:1], off offset:1088
	global_load_dwordx4 v[32:35], v[0:1], off offset:1120
	global_load_dwordx4 v[36:39], v[2:3], off offset:1088
	global_load_dwordx4 v[176:179], v[2:3], off offset:1120
	v_mov_b32_e32 v0, s24
	ds_read_b32 v194, v0 offset:1024
	v_cmp_lt_i32_e32 vcc, v208, v209
	s_cmp_eq_u32 s52, 0
	s_nop 0
	v_cndmask_b32_e32 v0, v207, v208, vcc
	v_lshlrev_b32_e32 v191, 2, v0
	s_cbranch_scc1 .LBB0_813
	s_min_u32 s13, s52, 8
	s_sub_i32 s52, s52, s13
	s_ashr_i32 s53, s52, 31
	s_lshl_b32 s14, s13, 6
	s_lshl_b64 s[54:55], s[52:53], 6
	s_add_u32 s54, s54, s20
	s_addc_u32 s55, s55, s21
	s_lshl_b32 s13, s43, 1
	s_and_b32 s43, s13, 0x380
	v_lshl_add_u64 v[0:1], s[54:55], 0, v[184:185]
	s_add_u32 s54, s38, s43
	s_addc_u32 s55, s39, 0
	s_mul_hi_i32 s13, s12, 0x1600000
	s_mul_i32 s12, s12, 0x1600000
	s_mul_hi_i32 s53, s52, 0xb0000
	s_mul_i32 s52, s52, 0xb0000
	v_mov_b64_e32 v[2:3], s[54:55]
	s_add_u32 s12, s12, s52
	v_mad_u64_u32 v[198:199], s[54:55], v0, s17, v[2:3]
	s_addc_u32 s13, s13, s53
	s_or_b32 s12, s12, s43
	v_mov_b32_e32 v233, 0
	s_waitcnt vmcnt(0)
	v_mov_b64_e32 v[112:113], v[176:177]
	v_mov_b64_e32 v[118:119], v[34:35]
	v_mov_b64_e32 v[126:127], v[38:39]
	v_mov_b64_e32 v[122:123], v[42:43]
	v_mov_b64_e32 v[130:131], v[46:47]
	v_mov_b64_e32 v[134:135], v[50:51]
	v_mov_b64_e32 v[142:143], v[58:59]
	v_mov_b64_e32 v[138:139], v[54:55]
	s_waitcnt lgkmcnt(0)
	v_mov_b32_e32 v196, v194
	v_mov_b32_e32 v197, v194
	v_add_u32_e32 v232, s25, v226
	v_mad_i32_i24 v199, v1, s17, v199
	v_lshl_add_u64 v[200:201], v[188:189], 0, s[12:13]
	v_mov_b32_e32 v234, 0xf149f2ca
	s_mov_b32 s43, 0
	v_mov_b32_e32 v16, 0
	v_mov_b32_e32 v17, v233
	v_mov_b32_e32 v18, v233
	v_mov_b32_e32 v19, v233
	v_mov_b32_e32 v20, v233
	v_mov_b32_e32 v21, v233
	v_mov_b32_e32 v22, v233
	v_mov_b32_e32 v23, v233
	v_mov_b32_e32 v24, v233
	v_mov_b32_e32 v25, v233
	v_mov_b32_e32 v26, v233
	v_mov_b32_e32 v27, v233
	v_mov_b32_e32 v28, v233
	v_mov_b32_e32 v29, v233
	v_mov_b32_e32 v30, v233
	v_mov_b32_e32 v31, v233
	v_mov_b32_e32 v0, 0
	v_mov_b32_e32 v1, v233
	v_mov_b32_e32 v2, v233
	v_mov_b32_e32 v3, v233
	v_mov_b32_e32 v4, v233
	v_mov_b32_e32 v5, v233
	v_mov_b32_e32 v6, v233
	v_mov_b32_e32 v7, v233
	v_mov_b32_e32 v8, v233
	v_mov_b32_e32 v9, v233
	v_mov_b32_e32 v10, v233
	v_mov_b32_e32 v11, v233
	v_mov_b32_e32 v12, v233
	v_mov_b32_e32 v13, v233
	v_mov_b32_e32 v14, v233
	v_mov_b32_e32 v15, v233
	v_mov_b64_e32 v[114:115], v[178:179]
	v_mov_b64_e32 v[116:117], v[32:33]
	v_mov_b64_e32 v[124:125], v[36:37]
	v_mov_b64_e32 v[120:121], v[40:41]
	v_mov_b64_e32 v[128:129], v[44:45]
	v_mov_b64_e32 v[132:133], v[48:49]
	v_mov_b64_e32 v[140:141], v[56:57]
	v_mov_b64_e32 v[136:137], v[52:53]
